# batch2: P3 PV V-fragment prefetch, packed f32 adds split to scalar in attention loops, P11 expert-index ds_bpermutes batched before gather issue
# speedup vs baseline: 1.1254x; 1.0107x over previous
; __device__ __forceinline__ f32x16 mfma32(bf16x8 a, bf16x8 b, f32x16 c) { return __builtin_amdgcn_mfma_f32_32x32x16_bf16(a, b, c, 0, 0, 0); }
; __device__ __forceinline__ int accrow(int reg, int hh) { return (reg & 3) + 8 * (reg >> 2) + 4 * hh; }
; template <int MODE>
; __device__ void attn_item(const Params& p, char* lds, int grp  , int b, int h, int qblk, int dry) {
;     ...
;       const char* kp0 = base + l31 * KSTR + comp * 128 + hh * 16;
;       {
;         bf16x8 kf0[DQ / 16], kf1[DQ / 16];
; #pragma unroll
;         for (int ks = 0; ks < DQ / 16; ++ks) kf0[ks] = *(const bf16x8*)(kp0 + ks * 32);
;         __builtin_amdgcn_sched_barrier(0);
; #pragma unroll
;         for (int ks = 0; ks < DQ / 16; ++ks) kf1[ks] = *(const bf16x8*)(kp0 + 32 * KSTR + ks * 32);
; #pragma unroll
;         for (int r = 0; r < 16; ++r) { S[0][r] = 0.f; S[1][r] = 0.f; }
; #pragma unroll
;         for (int ks = 0; ks < DQ / 16; ++ks) S[0] = mfma32(kf0[ks], qf[ks], S[0]);
; #pragma unroll
;         for (int ks = 0; ks < DQ / 16; ++ks) S[1] = mfma32(kf1[ks], qf[ks], S[1]);
;       }
;       if (MODE == 0) {
;         const int kpos0 = kt * 64;
;         if (kpos0 + 63 > qpos0 - 91) {
; #pragma unroll
;           for (int sub = 0; sub < 2; ++sub)
; #pragma unroll
;             for (int r = 0; r < 16; ++r) {
;               int rel = kpos0 + sub * 32 + accrow(r, hh) - qpos; rel = rel < -128 ? -128 : rel;
;               S[sub][r] += s_bt[rel + 128];
;             }
;         }
.LBB0_450:
	s_bitcmp1_b32 s27, 0
	s_cselect_b32 s27, 0x8c00, 0
	v_add_u32_e32 v64, s27, v193
	v_add3_u32 v220, v64, v194, v182
	ds_read_b128 v[64:67], v220
	ds_read_b128 v[68:71], v220 offset:32
	ds_read_b128 v[72:75], v220 offset:64
	ds_read_b128 v[76:79], v220 offset:96
	s_waitcnt lgkmcnt(3)
	v_mfma_f32_32x32x16_bf16 v[80:95], v[64:67], v[96:99], 0
	ds_read_b128 v[64:67], v220 offset:8704
	ds_read_b128 v[216:219], v220 offset:8736
	ds_read_b128 v[238:241], v220 offset:8768
	ds_read_b128 v[242:245], v220 offset:8800
	s_add_i32 s44, s24, -1
	s_cmp_le_i32 s44, s2
	s_waitcnt lgkmcnt(6)
	v_mfma_f32_32x32x16_bf16 v[80:95], v[68:71], v[100:103], v[80:95]
	s_waitcnt lgkmcnt(5)
	v_mfma_f32_32x32x16_bf16 v[80:95], v[72:75], v[104:107], v[80:95]
	s_waitcnt lgkmcnt(4)
	v_mfma_f32_32x32x16_bf16 v[80:95], v[76:79], v[108:111], v[80:95]
	s_waitcnt lgkmcnt(3)
	v_mfma_f32_32x32x16_bf16 v[64:79], v[64:67], v[96:99], 0
	s_waitcnt lgkmcnt(2)
	v_mfma_f32_32x32x16_bf16 v[64:79], v[216:219], v[100:103], v[64:79]
	s_waitcnt lgkmcnt(1)
	v_mfma_f32_32x32x16_bf16 v[64:79], v[238:241], v[104:107], v[64:79]
	s_waitcnt lgkmcnt(0)
	v_mfma_f32_32x32x16_bf16 v[64:79], v[242:245], v[108:111], v[64:79]
	s_cbranch_scc1 .LBB0_452
	v_add_u32_e32 v220, s24, v165
	v_subrev_u32_e32 v216, 64, v220
	v_max_i32_e32 v216, 0xffffff80, v216
	v_lshl_add_u32 v238, v216, 2, v210
	v_subrev_u32_e32 v216, 63, v220
	v_max_i32_e32 v216, 0xffffff80, v216
	v_lshl_add_u32 v239, v216, 2, v210
	v_subrev_u32_e32 v216, 62, v220
	v_max_i32_e32 v216, 0xffffff80, v216
	v_lshl_add_u32 v240, v216, 2, v210
	v_subrev_u32_e32 v216, 61, v220
	v_max_i32_e32 v216, 0xffffff80, v216
	v_lshl_add_u32 v241, v216, 2, v210
	v_subrev_u32_e32 v216, 56, v220
	v_max_i32_e32 v216, 0xffffff80, v216
	v_lshl_add_u32 v242, v216, 2, v210
	v_subrev_u32_e32 v216, 55, v220
	v_max_i32_e32 v216, 0xffffff80, v216
	v_lshl_add_u32 v243, v216, 2, v210
	v_subrev_u32_e32 v216, 54, v220
	v_max_i32_e32 v216, 0xffffff80, v216
	v_lshl_add_u32 v244, v216, 2, v210
	v_subrev_u32_e32 v216, 53, v220
	v_max_i32_e32 v216, 0xffffff80, v216
	v_lshl_add_u32 v245, v216, 2, v210
	v_subrev_u32_e32 v216, 48, v220
	v_subrev_u32_e32 v217, 47, v220
	v_subrev_u32_e32 v218, 46, v220
	v_subrev_u32_e32 v219, 45, v220
	v_subrev_u32_e32 v234, 40, v220
	v_subrev_u32_e32 v235, 39, v220
	v_subrev_u32_e32 v236, 38, v220
	v_subrev_u32_e32 v237, 37, v220
	v_max_i32_e32 v216, 0xffffff80, v216
	v_max_i32_e32 v217, 0xffffff80, v217
	v_max_i32_e32 v218, 0xffffff80, v218
	v_max_i32_e32 v219, 0xffffff80, v219
	v_max_i32_e32 v234, 0xffffff80, v234
	v_max_i32_e32 v235, 0xffffff80, v235
	v_max_i32_e32 v236, 0xffffff80, v236
	v_max_i32_e32 v237, 0xffffff80, v237
	v_lshl_add_u32 v216, v216, 2, v210
	v_lshl_add_u32 v217, v217, 2, v210
	v_lshl_add_u32 v218, v218, 2, v210
	v_lshl_add_u32 v219, v219, 2, v210
	v_lshl_add_u32 v234, v234, 2, v210
	v_lshl_add_u32 v235, v235, 2, v210
	v_lshl_add_u32 v236, v236, 2, v210
	v_lshl_add_u32 v237, v237, 2, v210
	ds_read_b32 v216, v216
	ds_read_b32 v217, v217
	ds_read_b32 v218, v218
	ds_read_b32 v219, v219
	ds_read_b32 v234, v234
	ds_read_b32 v235, v235
	ds_read_b32 v236, v236
	ds_read_b32 v237, v237
	ds_read_b32 v238, v238
	ds_read_b32 v239, v239
	ds_read_b32 v240, v240
	ds_read_b32 v241, v241
	ds_read_b32 v242, v242
	ds_read_b32 v243, v243
	ds_read_b32 v244, v244
	ds_read_b32 v245, v245
	s_waitcnt lgkmcnt(14)
	v_add_f32_e32 v88, v88, v216
	v_add_f32_e32 v89, v89, v217
	v_subrev_u32_e32 v216, 32, v220
	v_max_i32_e32 v216, 0xffffff80, v216
	s_waitcnt lgkmcnt(6)
	v_add_f32_e32 v80, v80, v238
	v_add_f32_e32 v81, v81, v239
	v_lshl_add_u32 v238, v216, 2, v210
	v_subrev_u32_e32 v216, 31, v220
	v_max_i32_e32 v216, 0xffffff80, v216
	v_lshl_add_u32 v239, v216, 2, v210
	v_subrev_u32_e32 v216, 30, v220
	v_max_i32_e32 v216, 0xffffff80, v216
	s_waitcnt lgkmcnt(4)
	v_add_f32_e32 v82, v82, v240
	v_add_f32_e32 v83, v83, v241
	v_lshl_add_u32 v240, v216, 2, v210
	v_subrev_u32_e32 v216, 29, v220
	v_max_i32_e32 v216, 0xffffff80, v216
	v_lshl_add_u32 v241, v216, 2, v210
	v_subrev_u32_e32 v216, 24, v220
	v_max_i32_e32 v216, 0xffffff80, v216
	s_waitcnt lgkmcnt(2)
	v_add_f32_e32 v84, v84, v242
	v_add_f32_e32 v85, v85, v243
	v_lshl_add_u32 v242, v216, 2, v210
	v_subrev_u32_e32 v216, 23, v220
	v_max_i32_e32 v216, 0xffffff80, v216
	v_lshl_add_u32 v243, v216, 2, v210
	v_subrev_u32_e32 v216, 22, v220
	v_max_i32_e32 v216, 0xffffff80, v216
	s_waitcnt lgkmcnt(0)
	v_add_f32_e32 v86, v86, v244
	v_add_f32_e32 v87, v87, v245
	v_lshl_add_u32 v244, v216, 2, v210
	v_subrev_u32_e32 v216, 21, v220
	v_max_i32_e32 v216, 0xffffff80, v216
	v_add_f32_e32 v94, v94, v236
	v_add_f32_e32 v95, v95, v237
	v_add_f32_e32 v92, v92, v234
	v_add_f32_e32 v93, v93, v235
	v_add_f32_e32 v90, v90, v218
	v_add_f32_e32 v91, v91, v219
	v_lshl_add_u32 v245, v216, 2, v210
	v_add_u32_e32 v216, -16, v220
	v_add_u32_e32 v217, -15, v220
	v_add_u32_e32 v218, -14, v220
	v_add_u32_e32 v219, -13, v220
	v_add_u32_e32 v234, -8, v220
	v_add_u32_e32 v235, -7, v220
	v_add_u32_e32 v236, -6, v220
	v_max_i32_e32 v216, 0xffffff80, v216
	v_max_i32_e32 v217, 0xffffff80, v217
	v_max_i32_e32 v218, 0xffffff80, v218
	v_max_i32_e32 v219, 0xffffff80, v219
	v_max_i32_e32 v234, 0xffffff80, v234
	v_max_i32_e32 v235, 0xffffff80, v235
	v_max_i32_e32 v236, 0xffffff80, v236
	v_add_u32_e32 v220, -5, v220
	v_lshl_add_u32 v216, v216, 2, v210
	v_lshl_add_u32 v217, v217, 2, v210
	v_lshl_add_u32 v218, v218, 2, v210
	v_lshl_add_u32 v219, v219, 2, v210
	v_lshl_add_u32 v234, v234, 2, v210
	v_lshl_add_u32 v235, v235, 2, v210
	v_lshl_add_u32 v236, v236, 2, v210
	v_max_i32_e32 v220, 0xffffff80, v220
	v_lshl_add_u32 v220, v220, 2, v210
	ds_read_b32 v216, v216
	ds_read_b32 v217, v217
	ds_read_b32 v218, v218
	ds_read_b32 v219, v219
	ds_read_b32 v234, v234
	ds_read_b32 v235, v235
	ds_read_b32 v236, v236
	ds_read_b32 v237, v220
	ds_read_b32 v238, v238
	ds_read_b32 v239, v239
	ds_read_b32 v240, v240
	ds_read_b32 v241, v241
	ds_read_b32 v242, v242
	ds_read_b32 v243, v243
	ds_read_b32 v244, v244
	ds_read_b32 v245, v245
	s_waitcnt lgkmcnt(8)
	v_add_f32_e32 v78, v78, v236
	v_add_f32_e32 v79, v79, v237
	v_add_f32_e32 v76, v76, v234
	v_add_f32_e32 v77, v77, v235
	v_add_f32_e32 v74, v74, v218
	v_add_f32_e32 v75, v75, v219
	v_add_f32_e32 v72, v72, v216
	v_add_f32_e32 v73, v73, v217
	s_waitcnt lgkmcnt(0)
	v_add_f32_e32 v70, v70, v244
	v_add_f32_e32 v71, v71, v245
	v_add_f32_e32 v68, v68, v242
	v_add_f32_e32 v69, v69, v243
	v_add_f32_e32 v66, v66, v240
	v_add_f32_e32 v67, v67, v241
	v_add_f32_e32 v64, v64, v238
	v_add_f32_e32 v65, v65, v239

; __device__ __forceinline__ unsigned pk2(float lo, float hi) { f32v2_t v = {lo, hi}; bf16v2_t r = __builtin_convertvector(v, bf16v2_t); return __builtin_bit_cast(unsigned, r); }
; __device__ __forceinline__ f32x16 mfma32(bf16x8 a, bf16x8 b, f32x16 c) { return __builtin_amdgcn_mfma_f32_32x32x16_bf16(a, b, c, 0, 0, 0); }
; template <int MODE>
; __device__ void attn_item(const Params& p, char* lds, int grp  , int b, int h, int qblk, int dry) {
;     ...
;       if (MODE == 0 && more) { lwriteK((kt + 1) & 1); gloadV(kt + 1); }
;       f32v2_t ps2 = {0.f, 0.f}; const f32v2_t m2 = {m, m};
;       const char* vp0 = base + KBYTES + l31 * 144 + hh * 16;
; #pragma unroll
;       for (int sub = 0; sub < 2; ++sub) {
; #pragma unroll
;         for (int r = 0; r < 16; r += 2) {
;           f32v2_t v = (f32v2_t){S[sub][r], S[sub][r + 1]} - m2;
;           v[0] = __builtin_amdgcn_exp2f(v[0]); v[1] = __builtin_amdgcn_exp2f(v[1]);
;           S[sub][r] = v[0]; S[sub][r + 1] = v[1]; ps2 += v;
;         }
; #pragma unroll
;         for (int s = 0; s < 2; ++s) {
;           u32x4 w;
;           w.x = pk2(S[sub][8 * s + 0], S[sub][8 * s + 1]); w.y = pk2(S[sub][8 * s + 2], S[sub][8 * s + 3]);
;           w.z = pk2(S[sub][8 * s + 4], S[sub][8 * s + 5]); w.w = pk2(S[sub][8 * s + 6], S[sub][8 * s + 7]);
;           const bf16x8 pf = __builtin_bit_cast(bf16x8, w);
; #pragma unroll
;           for (int blk = 0; blk < DV / 32; ++blk) {
;             bf16x8 vf = *(const bf16x8*)(vp0 + blk * 32 * 144 + sub * 64 + s * 32);
;             O[blk] = mfma32(vf, pf, O[blk]);
;           }
;         }
;       }
;       l += ps2[0] + ps2[1];
.LBB0_456:
	v_sub_f32_e32 v80, v80, v168
	v_sub_f32_e32 v81, v81, v168
	v_sub_f32_e32 v82, v82, v168
	v_sub_f32_e32 v83, v83, v168
	v_sub_f32_e32 v84, v84, v168
	v_sub_f32_e32 v85, v85, v168
	v_sub_f32_e32 v86, v86, v168
	v_sub_f32_e32 v87, v87, v168
	v_add3_u32 v216, s27, v195, v182
	v_exp_f32_e32 v80, v80
	v_exp_f32_e32 v81, v81
	v_exp_f32_e32 v82, v82
	v_exp_f32_e32 v83, v83
	v_exp_f32_e32 v84, v84
	v_exp_f32_e32 v85, v85
	v_exp_f32_e32 v86, v86
	v_exp_f32_e32 v87, v87
	ds_read_b128 v[238:241], v216 offset:17408
	ds_read_b128 v[242:245], v216 offset:17440
	v_cvt_pk_bf16_f32 v234, v80, v81
	v_cvt_pk_bf16_f32 v235, v82, v83
	v_cvt_pk_bf16_f32 v236, v84, v85
	v_cvt_pk_bf16_f32 v237, v86, v87
	v_sub_f32_e32 v88, v88, v168
	v_sub_f32_e32 v89, v89, v168
	v_sub_f32_e32 v90, v90, v168
	v_sub_f32_e32 v91, v91, v168
	s_waitcnt lgkmcnt(1)
	v_mfma_f32_32x32x16_bf16 v[32:47], v[238:241], v[234:237], v[32:47]
	ds_read_b128 v[238:241], v216 offset:22016
	v_add_f32_e64 v92, v92, -v168
	v_add_f32_e64 v93, v93, -v168
	v_add_f32_e64 v94, v94, -v168
	v_add_f32_e64 v95, v95, -v168
	v_exp_f32_e32 v88, v88
	v_exp_f32_e32 v89, v89
	v_exp_f32_e32 v90, v90
	v_exp_f32_e32 v91, v91
	s_waitcnt lgkmcnt(0)
	v_mfma_f32_32x32x16_bf16 v[48:63], v[238:241], v[234:237], v[48:63]
	ds_read_b128 v[238:241], v216 offset:26624
	v_exp_f32_e32 v92, v92
	v_exp_f32_e32 v93, v93
	v_exp_f32_e32 v94, v94
	v_exp_f32_e32 v95, v95
	v_sub_f32_e32 v64, v64, v168
	v_sub_f32_e32 v65, v65, v168
	v_sub_f32_e32 v66, v66, v168
	v_sub_f32_e32 v67, v67, v168
	s_waitcnt lgkmcnt(0)
	v_mfma_f32_32x32x16_bf16 v[0:15], v[238:241], v[234:237], v[0:15]
	ds_read_b128 v[238:241], v216 offset:31232
	v_add_f32_e64 v68, v68, -v168
	v_add_f32_e64 v69, v69, -v168
	v_add_f32_e64 v70, v70, -v168
	v_add_f32_e64 v71, v71, -v168
	v_exp_f32_e32 v64, v64
	v_exp_f32_e32 v65, v65
	v_exp_f32_e32 v66, v66
	v_exp_f32_e32 v67, v67
	s_waitcnt lgkmcnt(0)
	v_mfma_f32_32x32x16_bf16 v[16:31], v[238:241], v[234:237], v[16:31]
	ds_read_b128 v[238:241], v216 offset:22048
	v_cvt_pk_bf16_f32 v234, v88, v89
	v_cvt_pk_bf16_f32 v235, v90, v91
	v_cvt_pk_bf16_f32 v236, v92, v93
	v_cvt_pk_bf16_f32 v237, v94, v95
	v_exp_f32_e32 v68, v68
	v_exp_f32_e32 v69, v69
	s_waitcnt lgkmcnt(0)
	v_mfma_f32_32x32x16_bf16 v[48:63], v[238:241], v[234:237], v[48:63]
	ds_read_b128 v[238:241], v216 offset:26656
	v_exp_f32_e32 v70, v70
	v_exp_f32_e32 v71, v71
	v_sub_f32_e32 v72, v72, v168
	v_sub_f32_e32 v73, v73, v168
	v_sub_f32_e32 v74, v74, v168
	v_sub_f32_e32 v75, v75, v168
	v_sub_f32_e32 v76, v76, v168
	v_sub_f32_e32 v77, v77, v168
	v_sub_f32_e32 v78, v78, v168
	v_sub_f32_e32 v79, v79, v168
	s_waitcnt lgkmcnt(0)
	v_mfma_f32_32x32x16_bf16 v[0:15], v[238:241], v[234:237], v[0:15]
	ds_read_b128 v[238:241], v216 offset:31264
	v_exp_f32_e32 v72, v72
	v_exp_f32_e32 v73, v73
	v_exp_f32_e32 v74, v74
	v_exp_f32_e32 v75, v75
	v_exp_f32_e32 v76, v76
	v_exp_f32_e32 v77, v77
	s_waitcnt lgkmcnt(0)
	v_mfma_f32_32x32x16_bf16 v[16:31], v[238:241], v[234:237], v[16:31]
	ds_read_b128 v[238:241], v216 offset:17472
	v_exp_f32_e32 v78, v78
	v_exp_f32_e32 v79, v79
	s_and_b64 vcc, exec, s[44:45]
	v_mfma_f32_32x32x16_bf16 v[32:47], v[242:245], v[234:237], v[32:47]
	ds_read_b128 v[242:245], v216 offset:22080
	v_cvt_pk_bf16_f32 v234, v64, v65
	v_cvt_pk_bf16_f32 v235, v66, v67
	v_cvt_pk_bf16_f32 v236, v68, v69
	v_cvt_pk_bf16_f32 v237, v70, v71
	s_waitcnt lgkmcnt(1)
	s_nop 0
	v_mfma_f32_32x32x16_bf16 v[32:47], v[238:241], v[234:237], v[32:47]
	ds_read_b128 v[238:241], v216 offset:26688
	s_waitcnt lgkmcnt(1)
	v_mfma_f32_32x32x16_bf16 v[48:63], v[242:245], v[234:237], v[48:63]
	ds_read_b128 v[242:245], v216 offset:31296
	s_waitcnt lgkmcnt(1)
	v_mfma_f32_32x32x16_bf16 v[0:15], v[238:241], v[234:237], v[0:15]
	ds_read_b128 v[238:241], v216 offset:17504
	s_waitcnt lgkmcnt(1)
	v_mfma_f32_32x32x16_bf16 v[16:31], v[242:245], v[234:237], v[16:31]
	ds_read_b128 v[242:245], v216 offset:22112
	v_cvt_pk_bf16_f32 v234, v72, v73
	v_cvt_pk_bf16_f32 v235, v74, v75
	v_cvt_pk_bf16_f32 v236, v76, v77
	v_cvt_pk_bf16_f32 v237, v78, v79
	s_waitcnt lgkmcnt(1)
	s_nop 0
	v_mfma_f32_32x32x16_bf16 v[32:47], v[238:241], v[234:237], v[32:47]
	ds_read_b128 v[238:241], v216 offset:26720
	s_waitcnt lgkmcnt(1)
	v_mfma_f32_32x32x16_bf16 v[48:63], v[242:245], v[234:237], v[48:63]
	ds_read_b128 v[216:219], v216 offset:31328
	s_waitcnt lgkmcnt(1)
	v_mfma_f32_32x32x16_bf16 v[0:15], v[238:241], v[234:237], v[0:15]
	s_waitcnt lgkmcnt(0)
	v_mfma_f32_32x32x16_bf16 v[16:31], v[216:219], v[234:237], v[16:31]
	s_cbranch_vccnz .LBB0_458
	s_bitcmp1_b32 s3, 0
	s_cselect_b32 s0, 0x8c00, 0
	v_add3_u32 v216, s0, v179, v187
	v_add3_u32 v217, s0, v190, v187
	v_add3_u32 v218, s0, v191, v187
	v_add3_u32 v219, s0, v192, v187
	s_waitcnt vmcnt(3)
	ds_write_b128 v216, v[128:131] offset:17408
	s_waitcnt vmcnt(2)
	ds_write_b128 v217, v[132:135] offset:17408
	s_waitcnt vmcnt(1)
	ds_write_b128 v218, v[136:139] offset:17408
	s_waitcnt vmcnt(0)
	ds_write_b128 v219, v[140:143] offset:17408
.LBB0_458:
	v_add_f32_e32 v80, 0, v80
	v_add_f32_e32 v81, 0, v81
	s_add_i32 s24, s24, 64
	v_add_f32_e32 v80, v82, v80
	v_add_f32_e32 v81, v83, v81
	s_add_u32 s50, s50, 0x22000
	v_add_f32_e32 v80, v84, v80
	v_add_f32_e32 v81, v85, v81
	s_addc_u32 s51, s51, 0
	v_add_f32_e32 v80, v86, v80
	v_add_f32_e32 v81, v87, v81
	s_cmp_eq_u32 s26, s3
	v_add_f32_e32 v80, v88, v80
	v_add_f32_e32 v81, v89, v81
	s_waitcnt lgkmcnt(0)
	v_add_f32_e32 v80, v90, v80
	v_add_f32_e32 v81, v91, v81
	s_barrier
	v_add_f32_e32 v80, v92, v80
	v_add_f32_e32 v81, v93, v81
	v_add_f32_e32 v80, v94, v80
	v_add_f32_e32 v81, v95, v81
	v_add_f32_e32 v64, v64, v80
	v_add_f32_e32 v65, v65, v81
	v_add_f32_e32 v64, v66, v64
	v_add_f32_e32 v65, v67, v65
	v_add_f32_e32 v64, v68, v64
	v_add_f32_e32 v65, v69, v65
	v_add_f32_e32 v64, v70, v64
	v_add_f32_e32 v65, v71, v65
	v_add_f32_e32 v64, v72, v64
	v_add_f32_e32 v65, v73, v65
	v_add_f32_e32 v64, v74, v64
	v_add_f32_e32 v65, v75, v65
	v_add_f32_e32 v64, v76, v64
	v_add_f32_e32 v65, v77, v65
	v_add_f32_e32 v64, v78, v64
	v_add_f32_e32 v65, v79, v65
	v_add_f32_e32 v64, v64, v65
	v_add_f32_e32 v161, v161, v64
	s_cbranch_scc1 .LBB0_460
	s_mov_b32 s27, s3
	s_branch .LBB0_448

; __device__ __forceinline__ unsigned pk2(float lo, float hi) { f32v2_t v = {lo, hi}; bf16v2_t r = __builtin_convertvector(v, bf16v2_t); return __builtin_bit_cast(unsigned, r); }
; __device__ __forceinline__ f32x16 mfma32(bf16x8 a, bf16x8 b, f32x16 c) { return __builtin_amdgcn_mfma_f32_32x32x16_bf16(a, b, c, 0, 0, 0); }
; __device__ void attn_item_mla(const Params& p, char* lds, int grp, int b, int h, int qblk, int dry) {
;     ...
;           f32v2_t ps2 = {0.f, 0.f}; const f32v2_t m2 = {m[qs], m[qs]};
; #pragma unroll
;           for (int r = 0; r < 16; r += 2) {
;             f32v2_t v = (f32v2_t){S[qs][r], S[qs][r + 1]} - m2;
;             v[0] = __builtin_amdgcn_exp2f(v[0]); v[1] = __builtin_amdgcn_exp2f(v[1]);
;             S[qs][r] = v[0]; S[qs][r + 1] = v[1]; ps2 += v;
;           }
;           l[qs] += ps2[0] + ps2[1];
;         }
; #pragma unroll
;         for (int s2 = 0; s2 < 2; ++s2) {
;           u32x4 w0, w1;
;           w0.x = pk2(S[0][8 * s2 + 0], S[0][8 * s2 + 1]); w0.y = pk2(S[0][8 * s2 + 2], S[0][8 * s2 + 3]);
;           w0.z = pk2(S[0][8 * s2 + 4], S[0][8 * s2 + 5]); w0.w = pk2(S[0][8 * s2 + 6], S[0][8 * s2 + 7]);
;           w1.x = pk2(S[1][8 * s2 + 0], S[1][8 * s2 + 1]); w1.y = pk2(S[1][8 * s2 + 2], S[1][8 * s2 + 3]);
;           w1.z = pk2(S[1][8 * s2 + 4], S[1][8 * s2 + 5]); w1.w = pk2(S[1][8 * s2 + 6], S[1][8 * s2 + 7]);
;           const bf16x8 pf0 = __builtin_bit_cast(bf16x8, w0), pf1 = __builtin_bit_cast(bf16x8, w1);
; #pragma unroll
;           for (int blk = 0; blk < 2; ++blk) {
;             const bf16x8 vf = *(const bf16x8*)(vp0 + blk * 32 * 144 + sub * 64 + s2 * 32);
;             O[0][blk] = mfma32(vf, pf0, O[0][blk]);
;             O[1][blk] = mfma32(vf, pf1, O[1][blk]);
;           }
;         }
.LBB0_707:
	v_sub_f32_e32 v2, v96, v0
	v_sub_f32_e32 v3, v97, v0
	v_sub_f32_e32 v4, v98, v0
	v_sub_f32_e32 v5, v99, v0
	v_exp_f32_e32 v10, v2
	v_exp_f32_e32 v11, v3
	v_exp_f32_e32 v12, v4
	v_exp_f32_e32 v13, v5
	v_sub_f32_e32 v4, v100, v0
	v_sub_f32_e32 v5, v101, v0
	v_add_f32_e32 v2, 0, v10
	v_add_f32_e32 v3, 0, v11
	v_exp_f32_e32 v96, v4
	v_exp_f32_e32 v97, v5
	v_sub_f32_e32 v4, v102, v0
	v_sub_f32_e32 v5, v103, v0
	v_add_f32_e32 v2, v12, v2
	v_add_f32_e32 v3, v13, v3
	v_exp_f32_e32 v98, v4
	v_exp_f32_e32 v99, v5
	v_add_f32_e32 v2, v96, v2
	v_add_f32_e32 v3, v97, v3
	v_sub_f32_e32 v80, v80, v220
	v_sub_f32_e32 v81, v81, v220
	v_sub_f32_e32 v82, v82, v220
	v_sub_f32_e32 v83, v83, v220
	v_add_f32_e32 v4, v98, v2
	v_add_f32_e32 v5, v99, v3
	v_sub_f32_e32 v2, v104, v0
	v_sub_f32_e32 v3, v105, v0
	v_exp_f32_e32 v80, v80
	v_exp_f32_e32 v2, v2
	v_exp_f32_e32 v3, v3
	v_exp_f32_e32 v81, v81
	v_exp_f32_e32 v82, v82
	v_exp_f32_e32 v83, v83
	v_add_f32_e32 v6, v2, v4
	v_add_f32_e32 v7, v3, v5
	v_sub_f32_e32 v4, v106, v0
	v_sub_f32_e32 v5, v107, v0
	v_sub_f32_e32 v84, v84, v220
	v_sub_f32_e32 v85, v85, v220
	v_exp_f32_e32 v4, v4
	v_exp_f32_e32 v5, v5
	v_exp_f32_e32 v84, v84
	v_exp_f32_e32 v85, v85
	v_sub_f32_e32 v86, v86, v220
	v_sub_f32_e32 v87, v87, v220
	v_add_f32_e32 v8, v4, v6
	v_add_f32_e32 v9, v5, v7
	v_sub_f32_e32 v6, v108, v0
	v_sub_f32_e32 v7, v109, v0
	v_exp_f32_e32 v86, v86
	v_exp_f32_e32 v6, v6
	v_exp_f32_e32 v7, v7
	v_exp_f32_e32 v87, v87
	v_sub_f32_e32 v88, v88, v220
	v_sub_f32_e32 v89, v89, v220
	v_sub_f32_e32 v90, v90, v220
	v_sub_f32_e32 v91, v91, v220
	v_add_f32_e32 v100, v6, v8
	v_add_f32_e32 v101, v7, v9
	v_sub_f32_e32 v8, v110, v0
	v_sub_f32_e32 v9, v111, v0
	v_exp_f32_e32 v102, v88
	v_exp_f32_e32 v8, v8
	v_exp_f32_e32 v9, v9
	v_exp_f32_e32 v103, v89
	v_lshl_add_u32 v104, s16, 6, v243
	v_cvt_pk_bf16_f32 v10, v10, v11
	v_add_f32_e32 v100, v8, v100
	v_add_f32_e32 v101, v9, v101
	v_cvt_pk_bf16_f32 v11, v12, v13
	v_add_f32_e32 v100, v100, v101
	v_add_f32_e32 v14, v14, v100
	v_add_f32_e32 v100, 0, v80
	v_add_f32_e32 v101, 0, v81
	v_cvt_pk_bf16_f32 v80, v80, v81
	v_add_f32_e32 v100, v82, v100
	v_add_f32_e32 v101, v83, v101
	v_cvt_pk_bf16_f32 v81, v82, v83
	v_add_f32_e32 v100, v84, v100
	v_add_f32_e32 v101, v85, v101
	v_cvt_pk_bf16_f32 v82, v84, v85
	v_add_f32_e32 v100, v86, v100
	v_add_f32_e32 v101, v87, v101
	v_cvt_pk_bf16_f32 v83, v86, v87
	v_add_f32_e32 v88, v102, v100
	v_add_f32_e32 v89, v103, v101
	v_exp_f32_e32 v100, v90
	v_exp_f32_e32 v101, v91
	v_sub_f32_e32 v90, v92, v220
	v_sub_f32_e32 v91, v93, v220
	v_cvt_pk_bf16_f32 v12, v96, v97
	v_exp_f32_e32 v92, v90
	v_exp_f32_e32 v93, v91
	v_sub_f32_e32 v90, v94, v220
	v_sub_f32_e32 v91, v95, v220
	v_add_f32_e32 v88, v100, v88
	v_add_f32_e32 v89, v101, v89
	v_exp_f32_e32 v94, v90
	v_exp_f32_e32 v95, v91
	v_add_f32_e32 v88, v92, v88
	v_add_f32_e32 v89, v93, v89
	v_cvt_pk_bf16_f32 v13, v98, v99
	v_cvt_pk_bf16_f32 v2, v2, v3
	v_add_f32_e32 v88, v94, v88
	v_add_f32_e32 v89, v95, v89
	v_cvt_pk_bf16_f32 v3, v4, v5
	v_add_f32_e32 v88, v88, v89
	v_add_f32_e32 v195, v195, v88
	ds_read_b128 v[84:87], v104 offset:13312
	ds_read_b128 v[88:91], v104 offset:13344
	s_waitcnt lgkmcnt(1)
	v_mfma_f32_32x32x16_bf16 v[64:79], v[84:87], v[10:13], v[64:79]
	v_cvt_pk_bf16_f32 v4, v6, v7
	v_cvt_pk_bf16_f32 v5, v8, v9
	v_cvt_pk_bf16_f32 v6, v102, v103
	v_cvt_pk_bf16_f32 v7, v100, v101
	v_cvt_pk_bf16_f32 v8, v92, v93
	v_cvt_pk_bf16_f32 v9, v94, v95
	s_xor_b64 s[0:1], s[2:3], -1
	v_mfma_f32_32x32x16_bf16 v[32:47], v[84:87], v[80:83], v[32:47]
	ds_read_b128 v[84:87], v104 offset:17920
	s_mov_b32 s16, 1
	s_mov_b64 s[2:3], 0
	s_andn2_b64 vcc, exec, s[0:1]
	s_waitcnt lgkmcnt(0)
	v_mfma_f32_32x32x16_bf16 v[48:63], v[84:87], v[10:13], v[48:63]
	ds_read_b128 v[10:13], v104 offset:17952
	v_mfma_f32_32x32x16_bf16 v[16:31], v[84:87], v[80:83], v[16:31]
	v_mfma_f32_32x32x16_bf16 v[64:79], v[88:91], v[2:5], v[64:79]
	v_mfma_f32_32x32x16_bf16 v[32:47], v[88:91], v[6:9], v[32:47]
	s_waitcnt lgkmcnt(0)
	v_mfma_f32_32x32x16_bf16 v[48:63], v[10:13], v[2:5], v[48:63]
	v_mfma_f32_32x32x16_bf16 v[16:31], v[10:13], v[6:9], v[16:31]
	s_cbranch_vccz .LBB0_712

; __device__ __forceinline__ void peer_token_part(const Params& p, int t, int e_lo, int e_hi, float (&ov)[16], int lane) {
;     ...
;   for (int e0 = e_lo; e0 < e_hi; e0 += 8) {
;     u32x4 ua[8], va[8];
;     const int esel = (e0 & 63) + (lane & 7);
;     const float sul = __shfl(e0 < 64 ? mysu0 : mysu1, esel), gwl = __shfl(e0 < 64 ? myw0 : myw1, esel);
; #pragma unroll
;     for (int k = 0; k < 8; ++k) {
;       const int idx = __shfl(e0 < 64 ? myi0 : myi1, (e0 & 63) + k);
;       ua[k] = *(const u32x4*)(u8 + (size_t)idx * 2048 + lane * 16);
;       va[k] = *(const u32x4*)(v8 + (size_t)idx * 2048 + lane * 16);
;     }
;     float d[8];
; #pragma unroll
;     for (int k = 0; k < 8; ++k) {
;       f32v2_t acc = {0.f, 0.f};
; #pragma unroll
;       for (int i = 0; i < 4; ++i) {
;         const f32v2_t lo = __builtin_amdgcn_cvt_pk_f32_fp8((int)ua[k][i], false), hi = __builtin_amdgcn_cvt_pk_f32_fp8((int)ua[k][i], true);
;         acc = hv[2 * i] * lo + acc; acc = hv[2 * i + 1] * hi + acc;
;       }
;       d[k] = acc[0] + acc[1];
;     }
.LBB0_1171:
	s_add_i32 s52, s52, 8
	s_cmp_lt_u32 s52, 64
	s_cselect_b64 vcc, -1, 0
	s_and_b32 s2, s52, 56
	v_or_b32_e32 v1, s2, v137
	s_waitcnt vmcnt(0)
	v_cndmask_b32_e32 v0, v145, v146, vcc
	v_lshlrev_b32_e32 v1, 2, v1
	ds_bpermute_b32 v148, v1, v0
	v_cndmask_b32_e32 v0, v69, v67, vcc
	ds_bpermute_b32 v147, v1, v0
	v_or_b32_e32 v0, s2, v129
	v_cndmask_b32_e32 v16, v68, v66, vcc
	v_lshlrev_b32_e32 v17, 2, v0
	ds_bpermute_b32 v170, v17, v16
	ds_bpermute_b32 v171, v17, v16 offset:4
	ds_bpermute_b32 v172, v17, v16 offset:8
	ds_bpermute_b32 v173, v17, v16 offset:12
	ds_bpermute_b32 v174, v17, v16 offset:16
	ds_bpermute_b32 v175, v17, v16 offset:20
	ds_bpermute_b32 v176, v17, v16 offset:24
	ds_bpermute_b32 v177, v17, v16 offset:28
	v_mov_b32_e32 v179, 0
	s_waitcnt lgkmcnt(7)
	v_lshlrev_b32_e32 v178, 11, v170
	v_lshl_add_u64 v[182:183], v[84:85], 0, v[178:179]
	global_load_dwordx4 v[60:63], v[182:183], off
	v_lshl_add_u64 v[182:183], v[86:87], 0, v[178:179]
	global_load_dwordx4 v[28:31], v[182:183], off
	s_waitcnt lgkmcnt(6)
	v_lshlrev_b32_e32 v178, 11, v171
	v_lshl_add_u64 v[182:183], v[84:85], 0, v[178:179]
	global_load_dwordx4 v[56:59], v[182:183], off
	v_lshl_add_u64 v[182:183], v[86:87], 0, v[178:179]
	global_load_dwordx4 v[20:23], v[182:183], off
	s_waitcnt lgkmcnt(5)
	v_lshlrev_b32_e32 v178, 11, v172
	v_lshl_add_u64 v[182:183], v[84:85], 0, v[178:179]
	global_load_dwordx4 v[52:55], v[182:183], off
	v_lshl_add_u64 v[182:183], v[86:87], 0, v[178:179]
	global_load_dwordx4 v[24:27], v[182:183], off
	s_waitcnt lgkmcnt(4)
	v_lshlrev_b32_e32 v178, 11, v173
	v_lshl_add_u64 v[182:183], v[84:85], 0, v[178:179]
	global_load_dwordx4 v[48:51], v[182:183], off
	v_lshl_add_u64 v[182:183], v[86:87], 0, v[178:179]
	global_load_dwordx4 v[12:15], v[182:183], off
	s_waitcnt lgkmcnt(3)
	v_lshlrev_b32_e32 v178, 11, v174
	v_lshl_add_u64 v[182:183], v[84:85], 0, v[178:179]
	global_load_dwordx4 v[44:47], v[182:183], off
	v_lshl_add_u64 v[182:183], v[86:87], 0, v[178:179]
	global_load_dwordx4 v[8:11], v[182:183], off
	s_waitcnt lgkmcnt(2)
	v_lshlrev_b32_e32 v178, 11, v175
	v_lshl_add_u64 v[182:183], v[84:85], 0, v[178:179]
	global_load_dwordx4 v[36:39], v[182:183], off
	v_lshl_add_u64 v[182:183], v[86:87], 0, v[178:179]
	global_load_dwordx4 v[4:7], v[182:183], off
	s_waitcnt lgkmcnt(0)
	v_lshlrev_b32_e32 v178, 11, v176
	v_lshl_add_u64 v[182:183], v[84:85], 0, v[178:179]
	global_load_dwordx4 v[32:35], v[182:183], off
	v_lshl_add_u64 v[186:187], v[86:87], 0, v[178:179]
	v_lshlrev_b32_e32 v178, 11, v177
	v_lshl_add_u64 v[182:183], v[84:85], 0, v[178:179]
	global_load_dwordx4 v[40:43], v[182:183], off
	v_lshl_add_u64 v[16:17], v[86:87], 0, v[178:179]
	global_load_dwordx4 v[0:3], v[186:187], off
	s_waitcnt vmcnt(14)
	v_cvt_pk_f32_fp8_e32 v[150:151], v60
	v_cvt_pk_f32_fp8_sdwa v[152:153], v60 src0_sel:WORD_1
	global_load_dwordx4 v[16:19], v[16:17], off
	v_pk_fma_f32 v[150:151], v[150:151], v[102:103], 0 op_sel_hi:[1,1,0]
	s_nop 0
	v_pk_fma_f32 v[150:151], v[152:153], v[98:99], v[150:151]
	v_cvt_pk_f32_fp8_e32 v[152:153], v61
	v_cvt_pk_f32_fp8_sdwa v[60:61], v61 src0_sel:WORD_1
	v_pk_fma_f32 v[150:151], v[152:153], v[76:77], v[150:151]
	s_nop 0
	v_pk_fma_f32 v[60:61], v[60:61], v[72:73], v[150:151]
	v_cvt_pk_f32_fp8_e32 v[150:151], v62
	v_cvt_pk_f32_fp8_sdwa v[152:153], v62 src0_sel:WORD_1
	v_pk_fma_f32 v[60:61], v[150:151], v[100:101], v[60:61]
	v_cvt_pk_f32_fp8_e32 v[150:151], v63
	v_cvt_pk_f32_fp8_sdwa v[62:63], v63 src0_sel:WORD_1
	v_pk_fma_f32 v[60:61], v[152:153], v[78:79], v[60:61]
	s_nop 0
	v_pk_fma_f32 v[60:61], v[150:151], v[74:75], v[60:61]
	s_nop 0
	v_pk_fma_f32 v[60:61], v[62:63], v[70:71], v[60:61]
	s_waitcnt vmcnt(13)
	v_cvt_pk_f32_fp8_sdwa v[62:63], v56 src0_sel:WORD_1
	v_add_f32_e32 v149, v60, v61
	v_cvt_pk_f32_fp8_e32 v[60:61], v56
	v_pk_fma_f32 v[60:61], v[60:61], v[102:103], 0 op_sel_hi:[1,1,0]
	s_nop 0
	v_pk_fma_f32 v[60:61], v[62:63], v[98:99], v[60:61]
	v_cvt_pk_f32_fp8_e32 v[62:63], v57
	v_cvt_pk_f32_fp8_sdwa v[56:57], v57 src0_sel:WORD_1
	v_pk_fma_f32 v[60:61], v[62:63], v[76:77], v[60:61]
	s_nop 0
	v_pk_fma_f32 v[56:57], v[56:57], v[72:73], v[60:61]
	v_cvt_pk_f32_fp8_e32 v[60:61], v58
	v_cvt_pk_f32_fp8_sdwa v[62:63], v58 src0_sel:WORD_1
	v_pk_fma_f32 v[56:57], v[60:61], v[100:101], v[56:57]
	v_cvt_pk_f32_fp8_e32 v[60:61], v59
	v_cvt_pk_f32_fp8_sdwa v[58:59], v59 src0_sel:WORD_1
	v_pk_fma_f32 v[56:57], v[62:63], v[78:79], v[56:57]
	s_nop 0
	v_pk_fma_f32 v[56:57], v[60:61], v[74:75], v[56:57]
	s_nop 0
	v_pk_fma_f32 v[56:57], v[58:59], v[70:71], v[56:57]
	s_waitcnt vmcnt(11)
	v_cvt_pk_f32_fp8_sdwa v[58:59], v52 src0_sel:WORD_1
	v_add_f32_e32 v60, v56, v57
	v_cvt_pk_f32_fp8_e32 v[56:57], v52
	v_pk_fma_f32 v[56:57], v[56:57], v[102:103], 0 op_sel_hi:[1,1,0]
	s_nop 0
	v_pk_fma_f32 v[56:57], v[58:59], v[98:99], v[56:57]
	v_cvt_pk_f32_fp8_e32 v[58:59], v53
	v_cvt_pk_f32_fp8_sdwa v[52:53], v53 src0_sel:WORD_1
	v_pk_fma_f32 v[56:57], v[58:59], v[76:77], v[56:57]
	s_nop 0
	v_pk_fma_f32 v[52:53], v[52:53], v[72:73], v[56:57]
	v_cvt_pk_f32_fp8_e32 v[56:57], v54
	v_cvt_pk_f32_fp8_sdwa v[58:59], v54 src0_sel:WORD_1
	v_pk_fma_f32 v[52:53], v[56:57], v[100:101], v[52:53]
	v_cvt_pk_f32_fp8_e32 v[56:57], v55
	v_cvt_pk_f32_fp8_sdwa v[54:55], v55 src0_sel:WORD_1
	v_pk_fma_f32 v[52:53], v[58:59], v[78:79], v[52:53]
	s_nop 0
	v_pk_fma_f32 v[52:53], v[56:57], v[74:75], v[52:53]
	s_nop 0
	v_pk_fma_f32 v[52:53], v[54:55], v[70:71], v[52:53]
	s_waitcnt vmcnt(9)
; __device__ __forceinline__ void peer_token_part(const Params& p, int t, int e_lo, int e_hi, float (&ov)[16], int lane) {
;     ...
;     float d[8];
; #pragma unroll
;     for (int k = 0; k < 8; ++k) {
;       f32v2_t acc = {0.f, 0.f};
; #pragma unroll
;       for (int i = 0; i < 4; ++i) {
;         const f32v2_t lo = __builtin_amdgcn_cvt_pk_f32_fp8((int)ua[k][i], false), hi = __builtin_amdgcn_cvt_pk_f32_fp8((int)ua[k][i], true);
;         acc = hv[2 * i] * lo + acc; acc = hv[2 * i + 1] * hi + acc;
;       }
;       d[k] = acc[0] + acc[1];
;     }
;     float v4[4], v2[2], v1;
; #pragma unroll
;     for (int j = 0; j < 4; ++j) { const float keep = b0 ? d[2 * j + 1] : d[2 * j], send = b0 ? d[2 * j] : d[2 * j + 1]; v4[j] = keep + __shfl_xor(send, 1); }
; #pragma unroll
;     for (int j = 0; j < 2; ++j) { const float keep = b1 ? v4[2 * j + 1] : v4[2 * j], send = b1 ? v4[2 * j] : v4[2 * j + 1]; v2[j] = keep + __shfl_xor(send, 2); }
;     { const float keep = b2 ? v2[1] : v2[0], send = b2 ? v2[0] : v2[1]; v1 = keep + __shfl_xor(send, 4); }
;     v1 += __shfl_xor(v1, 8); v1 += __shfl_xor(v1, 16); v1 += __shfl_xor(v1, 32);
;     const float dl = v1 * sul;
;     const float wl = gwl * (0.5f * dl * (1.f + erff(dl * 0.70710678118654752f)));
	v_cvt_pk_f32_fp8_sdwa v[54:55], v48 src0_sel:WORD_1
	v_add_f32_e32 v56, v52, v53
	v_cvt_pk_f32_fp8_e32 v[52:53], v48
	v_pk_fma_f32 v[52:53], v[52:53], v[102:103], 0 op_sel_hi:[1,1,0]
	s_nop 0
	v_pk_fma_f32 v[52:53], v[54:55], v[98:99], v[52:53]
	v_cvt_pk_f32_fp8_e32 v[54:55], v49
	v_cvt_pk_f32_fp8_sdwa v[48:49], v49 src0_sel:WORD_1
	v_pk_fma_f32 v[52:53], v[54:55], v[76:77], v[52:53]
	s_nop 0
	v_pk_fma_f32 v[48:49], v[48:49], v[72:73], v[52:53]
	v_cvt_pk_f32_fp8_e32 v[52:53], v50
	v_cvt_pk_f32_fp8_sdwa v[54:55], v50 src0_sel:WORD_1
	v_pk_fma_f32 v[48:49], v[52:53], v[100:101], v[48:49]
	v_cvt_pk_f32_fp8_e32 v[52:53], v51
	v_cvt_pk_f32_fp8_sdwa v[50:51], v51 src0_sel:WORD_1
	v_pk_fma_f32 v[48:49], v[54:55], v[78:79], v[48:49]
	s_nop 0
	v_pk_fma_f32 v[48:49], v[52:53], v[74:75], v[48:49]
	s_nop 0
	v_pk_fma_f32 v[48:49], v[50:51], v[70:71], v[48:49]
	s_waitcnt vmcnt(7)
	v_cvt_pk_f32_fp8_sdwa v[50:51], v44 src0_sel:WORD_1
	v_add_f32_e32 v52, v48, v49
	v_cvt_pk_f32_fp8_e32 v[48:49], v44
	v_pk_fma_f32 v[48:49], v[48:49], v[102:103], 0 op_sel_hi:[1,1,0]
	s_nop 0
	v_pk_fma_f32 v[48:49], v[50:51], v[98:99], v[48:49]
	v_cvt_pk_f32_fp8_e32 v[50:51], v45
	v_cvt_pk_f32_fp8_sdwa v[44:45], v45 src0_sel:WORD_1
	v_pk_fma_f32 v[48:49], v[50:51], v[76:77], v[48:49]
	s_nop 0
	v_pk_fma_f32 v[44:45], v[44:45], v[72:73], v[48:49]
	v_cvt_pk_f32_fp8_e32 v[48:49], v46
	v_cvt_pk_f32_fp8_sdwa v[50:51], v46 src0_sel:WORD_1
	v_pk_fma_f32 v[44:45], v[48:49], v[100:101], v[44:45]
	v_cvt_pk_f32_fp8_e32 v[48:49], v47
	v_cvt_pk_f32_fp8_sdwa v[46:47], v47 src0_sel:WORD_1
	v_pk_fma_f32 v[44:45], v[50:51], v[78:79], v[44:45]
	s_nop 0
	v_pk_fma_f32 v[44:45], v[48:49], v[74:75], v[44:45]
	s_nop 0
	v_pk_fma_f32 v[44:45], v[46:47], v[70:71], v[44:45]
	s_waitcnt vmcnt(5)
	v_cvt_pk_f32_fp8_sdwa v[46:47], v36 src0_sel:WORD_1
	v_add_f32_e32 v48, v44, v45
	v_cvt_pk_f32_fp8_e32 v[44:45], v36
	v_pk_fma_f32 v[44:45], v[44:45], v[102:103], 0 op_sel_hi:[1,1,0]
	s_nop 0
	v_pk_fma_f32 v[44:45], v[46:47], v[98:99], v[44:45]
	v_cvt_pk_f32_fp8_e32 v[46:47], v37
	v_cvt_pk_f32_fp8_sdwa v[36:37], v37 src0_sel:WORD_1
	v_pk_fma_f32 v[44:45], v[46:47], v[76:77], v[44:45]
	s_nop 0
	v_pk_fma_f32 v[36:37], v[36:37], v[72:73], v[44:45]
	v_cvt_pk_f32_fp8_e32 v[44:45], v38
	v_cvt_pk_f32_fp8_sdwa v[46:47], v38 src0_sel:WORD_1
	v_pk_fma_f32 v[36:37], v[44:45], v[100:101], v[36:37]
	v_cvt_pk_f32_fp8_e32 v[44:45], v39
	v_cvt_pk_f32_fp8_sdwa v[38:39], v39 src0_sel:WORD_1
	v_pk_fma_f32 v[36:37], v[46:47], v[78:79], v[36:37]
	s_nop 0
	v_pk_fma_f32 v[36:37], v[44:45], v[74:75], v[36:37]
	s_nop 0
	v_pk_fma_f32 v[36:37], v[38:39], v[70:71], v[36:37]
	s_waitcnt vmcnt(3)
	v_cvt_pk_f32_fp8_sdwa v[38:39], v32 src0_sel:WORD_1
	v_add_f32_e32 v44, v36, v37
	v_cvt_pk_f32_fp8_e32 v[36:37], v32
	v_pk_fma_f32 v[36:37], v[36:37], v[102:103], 0 op_sel_hi:[1,1,0]
	s_nop 0
	v_pk_fma_f32 v[36:37], v[38:39], v[98:99], v[36:37]
	v_cvt_pk_f32_fp8_e32 v[38:39], v33
	v_cvt_pk_f32_fp8_sdwa v[32:33], v33 src0_sel:WORD_1
	v_pk_fma_f32 v[36:37], v[38:39], v[76:77], v[36:37]
	s_nop 0
	v_pk_fma_f32 v[32:33], v[32:33], v[72:73], v[36:37]
	v_cvt_pk_f32_fp8_e32 v[36:37], v34
	v_cvt_pk_f32_fp8_sdwa v[38:39], v34 src0_sel:WORD_1
	v_pk_fma_f32 v[32:33], v[36:37], v[100:101], v[32:33]
	v_cvt_pk_f32_fp8_e32 v[36:37], v35
	v_cvt_pk_f32_fp8_sdwa v[34:35], v35 src0_sel:WORD_1
	v_pk_fma_f32 v[32:33], v[38:39], v[78:79], v[32:33]
	s_nop 0
	v_pk_fma_f32 v[32:33], v[36:37], v[74:75], v[32:33]
	s_waitcnt vmcnt(2)
	v_cvt_pk_f32_fp8_sdwa v[36:37], v41 src0_sel:WORD_1
	v_pk_fma_f32 v[32:33], v[34:35], v[70:71], v[32:33]
	v_cvt_pk_f32_fp8_sdwa v[34:35], v40 src0_sel:WORD_1
	v_add_f32_e32 v38, v32, v33
	v_cvt_pk_f32_fp8_e32 v[32:33], v40
	v_pk_fma_f32 v[32:33], v[32:33], v[102:103], 0 op_sel_hi:[1,1,0]
	s_nop 0
	v_pk_fma_f32 v[32:33], v[34:35], v[98:99], v[32:33]
	v_cvt_pk_f32_fp8_e32 v[34:35], v41
	v_pk_fma_f32 v[32:33], v[34:35], v[76:77], v[32:33]
	v_cvt_pk_f32_fp8_e32 v[34:35], v42
	v_pk_fma_f32 v[32:33], v[36:37], v[72:73], v[32:33]
	v_cvt_pk_f32_fp8_sdwa v[36:37], v42 src0_sel:WORD_1
	v_pk_fma_f32 v[32:33], v[34:35], v[100:101], v[32:33]
	v_cvt_pk_f32_fp8_e32 v[34:35], v43
	v_pk_fma_f32 v[32:33], v[36:37], v[78:79], v[32:33]
	v_cvt_pk_f32_fp8_sdwa v[36:37], v43 src0_sel:WORD_1
	v_pk_fma_f32 v[32:33], v[34:35], v[74:75], v[32:33]
	v_cndmask_b32_e64 v34, v149, v60, s[38:39]
	ds_bpermute_b32 v34, v95, v34
	v_cndmask_b32_e64 v35, v56, v52, s[38:39]
	v_pk_fma_f32 v[32:33], v[36:37], v[70:71], v[32:33]
	ds_bpermute_b32 v35, v95, v35
	v_cndmask_b32_e64 v36, v48, v44, s[38:39]
	ds_bpermute_b32 v36, v95, v36
	v_add_f32_e32 v32, v32, v33
	v_cndmask_b32_e64 v33, v60, v149, s[38:39]
	s_waitcnt lgkmcnt(2)
	v_add_f32_e32 v33, v33, v34
	v_cndmask_b32_e64 v34, v52, v56, s[38:39]
	s_waitcnt lgkmcnt(1)
	v_add_f32_e32 v34, v34, v35
	v_cndmask_b32_e64 v35, v44, v48, s[38:39]
	s_waitcnt lgkmcnt(0)
	v_add_f32_e32 v35, v35, v36
	v_cndmask_b32_e64 v36, v32, v38, s[38:39]
	v_cndmask_b32_e64 v32, v38, v32, s[38:39]
	ds_bpermute_b32 v32, v95, v32
	s_waitcnt lgkmcnt(0)
	v_add_f32_e32 v32, v36, v32
	v_cndmask_b32_e64 v36, v34, v33, s[40:41]
	v_cndmask_b32_e64 v33, v33, v34, s[40:41]
	v_cndmask_b32_e64 v34, v32, v35, s[40:41]
	v_cndmask_b32_e64 v32, v35, v32, s[40:41]
	ds_bpermute_b32 v33, v97, v33
	ds_bpermute_b32 v32, v97, v32
	s_waitcnt lgkmcnt(1)
	v_add_f32_e32 v33, v36, v33
	s_waitcnt lgkmcnt(0)
	v_add_f32_e32 v32, v34, v32
	v_cndmask_b32_e64 v34, v32, v33, s[42:43]
	v_cndmask_b32_e64 v32, v33, v32, s[42:43]
	ds_bpermute_b32 v32, v141, v32
	s_waitcnt lgkmcnt(0)
	v_add_f32_e32 v32, v34, v32
	ds_bpermute_b32 v33, v142, v32
	s_waitcnt lgkmcnt(0)
	v_add_f32_e32 v32, v32, v33
	ds_bpermute_b32 v33, v143, v32
	s_waitcnt lgkmcnt(0)
	v_add_f32_e32 v32, v32, v33
	ds_bpermute_b32 v33, v144, v32
	s_waitcnt lgkmcnt(0)
	v_add_f32_e32 v32, v32, v33
	v_mul_f32_e32 v32, v32, v148
	v_mul_f32_e32 v33, 0x3f3504f3, v32
	v_cmp_nlt_f32_e64 s[2:3], |v33|, 1.0
	s_and_saveexec_b64 s[54:55], s[2:3]
	s_xor_b64 s[2:3], exec, s[54:55]
	s_cbranch_execz .LBB0_1173
	v_fma_f32 v34, |v33|, s30, v138
	v_fma_f32 v34, |v33|, v34, s31
	v_fma_f32 v34, |v33|, v34, s34
	v_fma_f32 v34, |v33|, v34, s35
	v_fma_f32 v34, |v33|, v34, s82
	v_fma_f32 v34, |v33|, v34, s83
	v_fma_f32 v34, |v33|, v34, |v33|
	v_mul_f32_e32 v35, 0xbfb8aa3b, v34
	v_fma_f32 v36, v34, s90, -v35
	v_rndne_f32_e32 v37, v35
	v_fmac_f32_e32 v36, 0xb2a5705f, v34
	v_sub_f32_e32 v35, v35, v37
	v_add_f32_e32 v35, v35, v36
	v_cvt_i32_f32_e32 v36, v37
	v_exp_f32_e32 v35, v35
	v_cmp_nlt_f32_e32 vcc, s91, v34
	v_ldexp_f32 v35, v35, v36
	s_nop 0
	v_cndmask_b32_e32 v35, 0, v35, vcc
	v_cmp_ngt_f32_e32 vcc, s92, v34
	s_nop 1
	v_cndmask_b32_e32 v34, v139, v35, vcc
	v_sub_f32_e32 v34, 1.0, v34
